# Proj epilogue: preload the 8 ssq row values up front (stores stay in flight), on top of the GEMV and norm_first load batching
# speedup vs baseline: 1.0164x; 1.0022x over previous
; __device__ __forceinline__ float silu_f(float g) { return g * __builtin_amdgcn_rcpf(1.0f + __expf(-g)); }
;     __device__ __forceinline__ void operator()(const f32x4 (&acc)[2][2][4][2], const Unit& u, int wr, int wc, int fr, int fq) const {
;         const int r00 = u.pm * BM;
;         const int b = r00 < 32768 ? (r00 >> 11) : 16 + ((r00 - 32768) >> 12);
;         const int row0 = r00 + wr * 64 + fr; const int col0 = u.pn * BM + wc * 32 + 8 * fq;
;         const int mode = (u.pn < 2 || u.pn == 8 || u.pn == 9) ? 1 : ((u.pn >= 2 && u.pn < 6) ? 2 : 0);
;         const float* sp = shw + (size_t)b * 5632 + col0;
;         f32x4 sv[2][2];
; #pragma unroll
;         for (int bj = 0; bj < 2; ++bj) { sv[bj][0] = *(const f32x4*)(sp + bj * HALF); sv[bj][1] = *(const f32x4*)(sp + bj * HALF + 4); }
; #pragma unroll
;         for (int ai = 0; ai < 2; ++ai)
; #pragma unroll
;             for (int m = 0; m < 4; ++m) { const int row = row0 + ai * HALF + m * 16;
;                 const float rs = __builtin_amdgcn_rsqf(ssq[row] * (1.0f / 1024.0f) + 1e-6f);
;                 bf16_t* rowp = O + (size_t)row * 4224 + col0;
; #pragma unroll
;                 for (int bj = 0; bj < 2; ++bj) { f32x4 v0 = acc[ai][bj][m][0] * rs + sv[bj][0], v1 = acc[ai][bj][m][1] * rs + sv[bj][1];
;                     if (mode == 1) {
; #pragma unroll
;                         for (int e = 0; e < 4; ++e) { v0[e] = silu_f(v0[e]); v1[e] = silu_f(v1[e]); }
.LBB0_200:
	s_lshl_b32 s9, s0, 8
	s_add_i32 s17, s9, 0xffff8000
	v_add_u32_e32 v156, s9, v175
	s_lshr_b32 s17, s17, 12
	v_ashrrev_i32_e32 v157, 31, v156
	s_ashr_i32 s16, s0, 3
	s_add_i32 s17, s17, 16
	v_lshl_add_u64 v[158:159], v[156:157], 2, s[44:45]
	s_cmpk_lt_i32 s0, 0x80
	global_load_dword v157, v[158:159], off
	global_load_dword v192, v[158:159], off offset:64
	global_load_dword v193, v[158:159], off offset:128
	global_load_dword v194, v[158:159], off offset:192
	global_load_dword v195, v[158:159], off offset:512
	global_load_dword v196, v[158:159], off offset:576
	global_load_dword v197, v[158:159], off offset:640
	global_load_dword v198, v[158:159], off offset:704
	s_cselect_b32 s0, s16, s17
	s_and_b32 s16, s1, -2
	s_cmp_eq_u32 s16, 8
	s_cselect_b64 s[16:17], -1, 0
	s_cmp_lt_i32 s1, 6
	s_mul_hi_i32 s21, s0, 0x5800
	s_mulk_i32 s0, 0x5800
	v_lshl_or_b32 v154, s1, 8, v179
	s_cselect_b32 s39, 2, 0
	s_add_u32 s20, s22, s0
	s_addc_u32 s21, s65, s21
	v_ashrrev_i32_e32 v155, 31, v154
	v_lshl_add_u64 v[28:29], v[154:155], 2, s[20:21]
	global_load_dwordx4 v[44:47], v[28:29], off
	global_load_dwordx4 v[40:43], v[28:29], off offset:16
	global_load_dwordx4 v[24:27], v[28:29], off offset:528
	s_nop 0
	global_load_dwordx4 v[28:31], v[28:29], off offset:512
	s_cmp_lt_i32 s1, 2
	s_cselect_b64 s[0:1], -1, 0
	s_or_b64 s[0:1], s[0:1], s[16:17]
	s_and_b64 s[0:1], s[0:1], exec
	s_cselect_b32 s49, 1, s39
	s_cmp_gt_i32 s49, 1
	s_mov_b64 s[40:41], -1
	s_waitcnt vmcnt(0)
	v_fmamk_f32 v157, v157, 0x3a800000, v224
	v_rsq_f32_e32 v176, v157
	s_nop 0
	v_pk_fma_f32 v[142:143], v[142:143], v[176:177], v[46:47] op_sel_hi:[1,0,1]
	v_pk_fma_f32 v[140:141], v[140:141], v[176:177], v[44:45] op_sel_hi:[1,0,1]
	v_pk_fma_f32 v[138:139], v[138:139], v[176:177], v[42:43] op_sel_hi:[1,0,1]
	v_pk_fma_f32 v[136:137], v[136:137], v[176:177], v[40:41] op_sel_hi:[1,0,1]
	s_cbranch_scc0 .LBB0_202
	v_mul_f32_e32 v177, 0xbfb8aa3b, v136
	v_exp_f32_e32 v177, v177
	v_mul_f32_e32 v181, 0xbfb8aa3b, v141
	v_exp_f32_e32 v182, v181
	v_mul_f32_e32 v181, 0xbfb8aa3b, v137
	v_exp_f32_e32 v183, v181
	v_add_f32_e32 v177, 1.0, v177
	v_rcp_f32_e32 v181, v177
	v_add_f32_e32 v177, 1.0, v182
	v_rcp_f32_e32 v182, v177
	v_add_f32_e32 v177, 1.0, v183
	v_mul_f32_e32 v183, 0xbfb8aa3b, v142
	v_exp_f32_e32 v184, v183
	v_mul_f32_e32 v183, 0xbfb8aa3b, v138
	v_exp_f32_e32 v185, v183
	v_rcp_f32_e32 v183, v177
	v_add_f32_e32 v177, 1.0, v184
	v_rcp_f32_e32 v184, v177
	v_add_f32_e32 v177, 1.0, v185
	v_mul_f32_e32 v185, 0xbfb8aa3b, v143
	v_mul_f32_e32 v157, 0xbfb8aa3b, v140
	v_exp_f32_e32 v186, v185
	v_mul_f32_e32 v185, 0xbfb8aa3b, v139
	v_exp_f32_e32 v157, v157
	v_exp_f32_e32 v188, v185
	v_rcp_f32_e32 v185, v177
	v_add_f32_e32 v177, 1.0, v186
	v_add_f32_e32 v157, 1.0, v157
	v_rcp_f32_e32 v187, v177
	v_add_f32_e32 v177, 1.0, v188
	v_rcp_f32_e32 v157, v157
	v_rcp_f32_e32 v186, v177
	s_mov_b64 s[40:41], 0

; __device__ __forceinline__ unsigned cvt_pk_bf16(float lo, float hi) { unsigned r; asm volatile("v_cvt_pk_bf16_f32 %0, %1, %2" : "=v"(r) : "v"(lo), "v"(hi)); return r; }
; __device__ __forceinline__ float silu_f(float g) { return g * __builtin_amdgcn_rcpf(1.0f + __expf(-g)); }
; __device__ __forceinline__ float sigm_f(float g) { return __builtin_amdgcn_rcpf(1.0f + __expf(-g)); }
;     __device__ __forceinline__ void operator()(const f32x4 (&acc)[2][2][4][2], const Unit& u, int wr, int wc, int fr, int fq) const {
;     ...
;             for (int m = 0; m < 4; ++m) { const int row = row0 + ai * HALF + m * 16;
;                 const float rs = __builtin_amdgcn_rsqf(ssq[row] * (1.0f / 1024.0f) + 1e-6f);
;                 bf16_t* rowp = O + (size_t)row * 4224 + col0;
; #pragma unroll
;                 for (int bj = 0; bj < 2; ++bj) { f32x4 v0 = acc[ai][bj][m][0] * rs + sv[bj][0], v1 = acc[ai][bj][m][1] * rs + sv[bj][1];
;                     if (mode == 1) {
; #pragma unroll
;                         for (int e = 0; e < 4; ++e) { v0[e] = silu_f(v0[e]); v1[e] = silu_f(v1[e]); }
;                     } else if (mode == 2) {
; #pragma unroll
;                         for (int e = 0; e < 4; ++e) { v0[e] = sigm_f(v0[e]); v1[e] = sigm_f(v1[e]); }
;                     }
;                     u32x4 w; w.x = cvt_pk_bf16(v0[0], v0[1]); w.y = cvt_pk_bf16(v0[2], v0[3]); w.z = cvt_pk_bf16(v1[0], v1[1]); w.w = cvt_pk_bf16(v1[2], v1[3]);
;                     *(u32x4*)(rowp + bj * HALF) = w; } }
.LBB0_212:
	v_cvt_pk_bf16_f32 v128, v138, v140
	v_cvt_pk_bf16_f32 v129, v142, v176
	v_cvt_pk_bf16_f32 v130, v139, v141
	v_cvt_pk_bf16_f32 v131, v143, v157
	global_store_dwordx4 v[136:137], v[128:131], off offset:256
	s_nop 0
	s_cmp_gt_i32 s49, 1
	s_mov_b64 s[40:41], -1
	v_fmamk_f32 v128, v192, 0x3a800000, v224
	v_rsq_f32_e32 v128, v128
	s_nop 0
	v_pk_fma_f32 v[126:127], v[126:127], v[128:129], v[46:47] op_sel_hi:[1,0,1]
	v_pk_fma_f32 v[124:125], v[124:125], v[128:129], v[44:45] op_sel_hi:[1,0,1]
	v_pk_fma_f32 v[122:123], v[122:123], v[128:129], v[42:43] op_sel_hi:[1,0,1]
	v_pk_fma_f32 v[120:121], v[120:121], v[128:129], v[40:41] op_sel_hi:[1,0,1]
	s_cbranch_scc0 .LBB0_214
	v_mul_f32_e32 v129, 0xbfb8aa3b, v124
	v_exp_f32_e32 v129, v129
	v_mul_f32_e32 v130, 0xbfb8aa3b, v120
	v_exp_f32_e32 v130, v130
	v_mul_f32_e32 v132, 0xbfb8aa3b, v121
	v_add_f32_e32 v129, 1.0, v129
	v_exp_f32_e32 v133, v132
	v_add_f32_e32 v131, 1.0, v130
	v_rcp_f32_e32 v130, v129
	v_mul_f32_e32 v129, 0xbfb8aa3b, v125
	v_exp_f32_e32 v129, v129
	v_rcp_f32_e32 v131, v131
	s_mov_b64 s[40:41], 0
	v_add_f32_e32 v129, 1.0, v129
	v_rcp_f32_e32 v132, v129
	v_add_f32_e32 v129, 1.0, v133
	v_mul_f32_e32 v133, 0xbfb8aa3b, v126
	v_exp_f32_e32 v134, v133
	v_mul_f32_e32 v133, 0xbfb8aa3b, v122
	v_exp_f32_e32 v135, v133
	v_rcp_f32_e32 v133, v129
	v_add_f32_e32 v129, 1.0, v134
	v_rcp_f32_e32 v134, v129
	v_add_f32_e32 v129, 1.0, v135
	v_mul_f32_e32 v135, 0xbfb8aa3b, v127
	v_exp_f32_e32 v136, v135
	v_mul_f32_e32 v135, 0xbfb8aa3b, v123
	v_exp_f32_e32 v138, v135
	v_rcp_f32_e32 v135, v129
	v_add_f32_e32 v129, 1.0, v136
	v_rcp_f32_e32 v137, v129
	v_add_f32_e32 v129, 1.0, v138
	v_rcp_f32_e32 v136, v129

; __device__ __forceinline__ unsigned cvt_pk_bf16(float lo, float hi) { unsigned r; asm volatile("v_cvt_pk_bf16_f32 %0, %1, %2" : "=v"(r) : "v"(lo), "v"(hi)); return r; }
; __device__ __forceinline__ float silu_f(float g) { return g * __builtin_amdgcn_rcpf(1.0f + __expf(-g)); }
; __device__ __forceinline__ float sigm_f(float g) { return __builtin_amdgcn_rcpf(1.0f + __expf(-g)); }
;     __device__ __forceinline__ void operator()(const f32x4 (&acc)[2][2][4][2], const Unit& u, int wr, int wc, int fr, int fq) const {
;     ...
;             for (int m = 0; m < 4; ++m) { const int row = row0 + ai * HALF + m * 16;
;                 const float rs = __builtin_amdgcn_rsqf(ssq[row] * (1.0f / 1024.0f) + 1e-6f);
;                 bf16_t* rowp = O + (size_t)row * 4224 + col0;
; #pragma unroll
;                 for (int bj = 0; bj < 2; ++bj) { f32x4 v0 = acc[ai][bj][m][0] * rs + sv[bj][0], v1 = acc[ai][bj][m][1] * rs + sv[bj][1];
;                     if (mode == 1) {
; #pragma unroll
;                         for (int e = 0; e < 4; ++e) { v0[e] = silu_f(v0[e]); v1[e] = silu_f(v1[e]); }
;                     } else if (mode == 2) {
; #pragma unroll
;                         for (int e = 0; e < 4; ++e) { v0[e] = sigm_f(v0[e]); v1[e] = sigm_f(v1[e]); }
;                     }
;                     u32x4 w; w.x = cvt_pk_bf16(v0[0], v0[1]); w.y = cvt_pk_bf16(v0[2], v0[3]); w.z = cvt_pk_bf16(v1[0], v1[1]); w.w = cvt_pk_bf16(v1[2], v1[3]);
;                     *(u32x4*)(rowp + bj * HALF) = w; } }
.LBB0_224:
	v_cvt_pk_bf16_f32 v112, v122, v124
	v_cvt_pk_bf16_f32 v113, v126, v129
	v_cvt_pk_bf16_f32 v114, v123, v125
	v_cvt_pk_bf16_f32 v115, v127, v128
	global_store_dwordx4 v[120:121], v[112:115], off offset:256
	s_nop 0
	s_cmp_gt_i32 s49, 1
	s_mov_b64 s[40:41], -1
	v_fmamk_f32 v112, v193, 0x3a800000, v224
	v_rsq_f32_e32 v112, v112
	s_nop 0
	v_pk_fma_f32 v[110:111], v[110:111], v[112:113], v[46:47] op_sel_hi:[1,0,1]
	v_pk_fma_f32 v[108:109], v[108:109], v[112:113], v[44:45] op_sel_hi:[1,0,1]
	v_pk_fma_f32 v[106:107], v[106:107], v[112:113], v[42:43] op_sel_hi:[1,0,1]
	v_pk_fma_f32 v[104:105], v[104:105], v[112:113], v[40:41] op_sel_hi:[1,0,1]
	s_cbranch_scc0 .LBB0_226
	v_mul_f32_e32 v113, 0xbfb8aa3b, v108
	v_exp_f32_e32 v113, v113
	v_mul_f32_e32 v114, 0xbfb8aa3b, v104
	v_exp_f32_e32 v114, v114
	v_mul_f32_e32 v116, 0xbfb8aa3b, v105
	v_add_f32_e32 v113, 1.0, v113
	v_exp_f32_e32 v117, v116
	v_add_f32_e32 v115, 1.0, v114
	v_rcp_f32_e32 v114, v113
	v_mul_f32_e32 v113, 0xbfb8aa3b, v109
	v_exp_f32_e32 v113, v113
	v_rcp_f32_e32 v115, v115
	s_mov_b64 s[40:41], 0
	v_add_f32_e32 v113, 1.0, v113
	v_rcp_f32_e32 v116, v113
	v_add_f32_e32 v113, 1.0, v117
	v_mul_f32_e32 v117, 0xbfb8aa3b, v110
	v_exp_f32_e32 v118, v117
	v_mul_f32_e32 v117, 0xbfb8aa3b, v106
	v_exp_f32_e32 v119, v117
	v_rcp_f32_e32 v117, v113
	v_add_f32_e32 v113, 1.0, v118
	v_rcp_f32_e32 v118, v113
	v_add_f32_e32 v113, 1.0, v119
	v_mul_f32_e32 v119, 0xbfb8aa3b, v111
	v_exp_f32_e32 v120, v119
	v_mul_f32_e32 v119, 0xbfb8aa3b, v107
	v_exp_f32_e32 v122, v119
	v_rcp_f32_e32 v119, v113
	v_add_f32_e32 v113, 1.0, v120
	v_rcp_f32_e32 v121, v113
	v_add_f32_e32 v113, 1.0, v122
	v_rcp_f32_e32 v120, v113

; __device__ __forceinline__ unsigned cvt_pk_bf16(float lo, float hi) { unsigned r; asm volatile("v_cvt_pk_bf16_f32 %0, %1, %2" : "=v"(r) : "v"(lo), "v"(hi)); return r; }
; __device__ __forceinline__ float silu_f(float g) { return g * __builtin_amdgcn_rcpf(1.0f + __expf(-g)); }
; __device__ __forceinline__ float sigm_f(float g) { return __builtin_amdgcn_rcpf(1.0f + __expf(-g)); }
;     __device__ __forceinline__ void operator()(const f32x4 (&acc)[2][2][4][2], const Unit& u, int wr, int wc, int fr, int fq) const {
;     ...
;             for (int m = 0; m < 4; ++m) { const int row = row0 + ai * HALF + m * 16;
;                 const float rs = __builtin_amdgcn_rsqf(ssq[row] * (1.0f / 1024.0f) + 1e-6f);
;                 bf16_t* rowp = O + (size_t)row * 4224 + col0;
; #pragma unroll
;                 for (int bj = 0; bj < 2; ++bj) { f32x4 v0 = acc[ai][bj][m][0] * rs + sv[bj][0], v1 = acc[ai][bj][m][1] * rs + sv[bj][1];
;                     if (mode == 1) {
; #pragma unroll
;                         for (int e = 0; e < 4; ++e) { v0[e] = silu_f(v0[e]); v1[e] = silu_f(v1[e]); }
;                     } else if (mode == 2) {
; #pragma unroll
;                         for (int e = 0; e < 4; ++e) { v0[e] = sigm_f(v0[e]); v1[e] = sigm_f(v1[e]); }
;                     }
;                     u32x4 w; w.x = cvt_pk_bf16(v0[0], v0[1]); w.y = cvt_pk_bf16(v0[2], v0[3]); w.z = cvt_pk_bf16(v1[0], v1[1]); w.w = cvt_pk_bf16(v1[2], v1[3]);
;                     *(u32x4*)(rowp + bj * HALF) = w; } }
.LBB0_236:
	v_cvt_pk_bf16_f32 v96, v106, v108
	v_cvt_pk_bf16_f32 v97, v110, v113
	v_cvt_pk_bf16_f32 v98, v107, v109
	v_cvt_pk_bf16_f32 v99, v111, v112
	global_store_dwordx4 v[104:105], v[96:99], off offset:256
	s_nop 0
	s_cmp_gt_i32 s49, 1
	s_mov_b64 s[40:41], -1
	v_fmamk_f32 v96, v194, 0x3a800000, v224
	v_rsq_f32_e32 v96, v96
	s_nop 0
	v_pk_fma_f32 v[94:95], v[94:95], v[96:97], v[46:47] op_sel_hi:[1,0,1]
	v_pk_fma_f32 v[92:93], v[92:93], v[96:97], v[44:45] op_sel_hi:[1,0,1]
	v_pk_fma_f32 v[90:91], v[90:91], v[96:97], v[42:43] op_sel_hi:[1,0,1]
	v_pk_fma_f32 v[88:89], v[88:89], v[96:97], v[40:41] op_sel_hi:[1,0,1]
	s_cbranch_scc0 .LBB0_238
	v_mul_f32_e32 v97, 0xbfb8aa3b, v92
	v_exp_f32_e32 v97, v97
	v_mul_f32_e32 v98, 0xbfb8aa3b, v88
	v_exp_f32_e32 v98, v98
	v_mul_f32_e32 v100, 0xbfb8aa3b, v89
	v_add_f32_e32 v97, 1.0, v97
	v_exp_f32_e32 v101, v100
	v_add_f32_e32 v99, 1.0, v98
	v_rcp_f32_e32 v98, v97
	v_mul_f32_e32 v97, 0xbfb8aa3b, v93
	v_exp_f32_e32 v97, v97
	v_rcp_f32_e32 v99, v99
	s_mov_b64 s[40:41], 0
	v_add_f32_e32 v97, 1.0, v97
	v_rcp_f32_e32 v100, v97
	v_add_f32_e32 v97, 1.0, v101
	v_mul_f32_e32 v101, 0xbfb8aa3b, v94
	v_exp_f32_e32 v102, v101
	v_mul_f32_e32 v101, 0xbfb8aa3b, v90
	v_exp_f32_e32 v103, v101
	v_rcp_f32_e32 v101, v97
	v_add_f32_e32 v97, 1.0, v102
	v_rcp_f32_e32 v102, v97
	v_add_f32_e32 v97, 1.0, v103
	v_mul_f32_e32 v103, 0xbfb8aa3b, v95
	v_exp_f32_e32 v104, v103
	v_mul_f32_e32 v103, 0xbfb8aa3b, v91
	v_exp_f32_e32 v106, v103
	v_rcp_f32_e32 v103, v97
	v_add_f32_e32 v97, 1.0, v104
	v_rcp_f32_e32 v105, v97
	v_add_f32_e32 v97, 1.0, v106
	v_rcp_f32_e32 v104, v97

; __device__ __forceinline__ unsigned cvt_pk_bf16(float lo, float hi) { unsigned r; asm volatile("v_cvt_pk_bf16_f32 %0, %1, %2" : "=v"(r) : "v"(lo), "v"(hi)); return r; }
; __device__ __forceinline__ float silu_f(float g) { return g * __builtin_amdgcn_rcpf(1.0f + __expf(-g)); }
; __device__ __forceinline__ float sigm_f(float g) { return __builtin_amdgcn_rcpf(1.0f + __expf(-g)); }
;     __device__ __forceinline__ void operator()(const f32x4 (&acc)[2][2][4][2], const Unit& u, int wr, int wc, int fr, int fq) const {
;     ...
;             for (int m = 0; m < 4; ++m) { const int row = row0 + ai * HALF + m * 16;
;                 const float rs = __builtin_amdgcn_rsqf(ssq[row] * (1.0f / 1024.0f) + 1e-6f);
;                 bf16_t* rowp = O + (size_t)row * 4224 + col0;
; #pragma unroll
;                 for (int bj = 0; bj < 2; ++bj) { f32x4 v0 = acc[ai][bj][m][0] * rs + sv[bj][0], v1 = acc[ai][bj][m][1] * rs + sv[bj][1];
;                     if (mode == 1) {
; #pragma unroll
;                         for (int e = 0; e < 4; ++e) { v0[e] = silu_f(v0[e]); v1[e] = silu_f(v1[e]); }
;                     } else if (mode == 2) {
; #pragma unroll
;                         for (int e = 0; e < 4; ++e) { v0[e] = sigm_f(v0[e]); v1[e] = sigm_f(v1[e]); }
;                     }
;                     u32x4 w; w.x = cvt_pk_bf16(v0[0], v0[1]); w.y = cvt_pk_bf16(v0[2], v0[3]); w.z = cvt_pk_bf16(v1[0], v1[1]); w.w = cvt_pk_bf16(v1[2], v1[3]);
;                     *(u32x4*)(rowp + bj * HALF) = w; } }
.LBB0_248:
	v_cvt_pk_bf16_f32 v80, v90, v92
	v_cvt_pk_bf16_f32 v81, v94, v97
	v_cvt_pk_bf16_f32 v82, v91, v93
	v_cvt_pk_bf16_f32 v83, v95, v96
	global_store_dwordx4 v[88:89], v[80:83], off offset:256
	s_nop 0
	s_cmp_gt_i32 s49, 1
	s_mov_b64 s[40:41], -1
	v_fmamk_f32 v80, v195, 0x3a800000, v224
	v_rsq_f32_e32 v80, v80
	s_nop 0
	v_pk_fma_f32 v[78:79], v[78:79], v[80:81], v[46:47] op_sel_hi:[1,0,1]
	v_pk_fma_f32 v[76:77], v[76:77], v[80:81], v[44:45] op_sel_hi:[1,0,1]
	v_pk_fma_f32 v[74:75], v[74:75], v[80:81], v[42:43] op_sel_hi:[1,0,1]
	v_pk_fma_f32 v[72:73], v[72:73], v[80:81], v[40:41] op_sel_hi:[1,0,1]
	s_cbranch_scc0 .LBB0_250
	v_mul_f32_e32 v81, 0xbfb8aa3b, v76
	v_exp_f32_e32 v81, v81
	v_mul_f32_e32 v82, 0xbfb8aa3b, v72
	v_exp_f32_e32 v82, v82
	v_mul_f32_e32 v84, 0xbfb8aa3b, v73
	v_add_f32_e32 v81, 1.0, v81
	v_exp_f32_e32 v85, v84
	v_add_f32_e32 v83, 1.0, v82
	v_rcp_f32_e32 v82, v81
	v_mul_f32_e32 v81, 0xbfb8aa3b, v77
	v_exp_f32_e32 v81, v81
	v_rcp_f32_e32 v83, v83
	s_mov_b64 s[40:41], 0
	v_add_f32_e32 v81, 1.0, v81
	v_rcp_f32_e32 v84, v81
	v_add_f32_e32 v81, 1.0, v85
	v_mul_f32_e32 v85, 0xbfb8aa3b, v78
	v_exp_f32_e32 v86, v85
	v_mul_f32_e32 v85, 0xbfb8aa3b, v74
	v_exp_f32_e32 v87, v85
	v_rcp_f32_e32 v85, v81
	v_add_f32_e32 v81, 1.0, v86
	v_rcp_f32_e32 v86, v81
	v_add_f32_e32 v81, 1.0, v87
	v_mul_f32_e32 v87, 0xbfb8aa3b, v79
	v_exp_f32_e32 v88, v87
	v_mul_f32_e32 v87, 0xbfb8aa3b, v75
	v_exp_f32_e32 v90, v87
	v_rcp_f32_e32 v87, v81
	v_add_f32_e32 v81, 1.0, v88
	v_rcp_f32_e32 v89, v81
	v_add_f32_e32 v81, 1.0, v90
	v_rcp_f32_e32 v88, v81

; __device__ __forceinline__ unsigned cvt_pk_bf16(float lo, float hi) { unsigned r; asm volatile("v_cvt_pk_bf16_f32 %0, %1, %2" : "=v"(r) : "v"(lo), "v"(hi)); return r; }
; __device__ __forceinline__ float silu_f(float g) { return g * __builtin_amdgcn_rcpf(1.0f + __expf(-g)); }
; __device__ __forceinline__ float sigm_f(float g) { return __builtin_amdgcn_rcpf(1.0f + __expf(-g)); }
;     __device__ __forceinline__ void operator()(const f32x4 (&acc)[2][2][4][2], const Unit& u, int wr, int wc, int fr, int fq) const {
;     ...
;             for (int m = 0; m < 4; ++m) { const int row = row0 + ai * HALF + m * 16;
;                 const float rs = __builtin_amdgcn_rsqf(ssq[row] * (1.0f / 1024.0f) + 1e-6f);
;                 bf16_t* rowp = O + (size_t)row * 4224 + col0;
; #pragma unroll
;                 for (int bj = 0; bj < 2; ++bj) { f32x4 v0 = acc[ai][bj][m][0] * rs + sv[bj][0], v1 = acc[ai][bj][m][1] * rs + sv[bj][1];
;                     if (mode == 1) {
; #pragma unroll
;                         for (int e = 0; e < 4; ++e) { v0[e] = silu_f(v0[e]); v1[e] = silu_f(v1[e]); }
;                     } else if (mode == 2) {
; #pragma unroll
;                         for (int e = 0; e < 4; ++e) { v0[e] = sigm_f(v0[e]); v1[e] = sigm_f(v1[e]); }
;                     }
;                     u32x4 w; w.x = cvt_pk_bf16(v0[0], v0[1]); w.y = cvt_pk_bf16(v0[2], v0[3]); w.z = cvt_pk_bf16(v1[0], v1[1]); w.w = cvt_pk_bf16(v1[2], v1[3]);
;                     *(u32x4*)(rowp + bj * HALF) = w; } }
.LBB0_260:
	v_cvt_pk_bf16_f32 v64, v74, v76
	v_cvt_pk_bf16_f32 v65, v78, v81
	v_cvt_pk_bf16_f32 v66, v75, v77
	v_cvt_pk_bf16_f32 v67, v79, v80
	global_store_dwordx4 v[72:73], v[64:67], off offset:256
	s_nop 0
	s_cmp_gt_i32 s49, 1
	s_mov_b64 s[40:41], -1
	v_fmamk_f32 v64, v196, 0x3a800000, v224
	v_rsq_f32_e32 v64, v64
	s_nop 0
	v_pk_fma_f32 v[62:63], v[62:63], v[64:65], v[46:47] op_sel_hi:[1,0,1]
	v_pk_fma_f32 v[60:61], v[60:61], v[64:65], v[44:45] op_sel_hi:[1,0,1]
	v_pk_fma_f32 v[58:59], v[58:59], v[64:65], v[42:43] op_sel_hi:[1,0,1]
	v_pk_fma_f32 v[56:57], v[56:57], v[64:65], v[40:41] op_sel_hi:[1,0,1]
	s_cbranch_scc0 .LBB0_262
	v_mul_f32_e32 v65, 0xbfb8aa3b, v60
	v_exp_f32_e32 v65, v65
	v_mul_f32_e32 v66, 0xbfb8aa3b, v56
	v_exp_f32_e32 v66, v66
	v_mul_f32_e32 v68, 0xbfb8aa3b, v57
	v_add_f32_e32 v65, 1.0, v65
	v_exp_f32_e32 v69, v68
	v_add_f32_e32 v67, 1.0, v66
	v_rcp_f32_e32 v66, v65
	v_mul_f32_e32 v65, 0xbfb8aa3b, v61
	v_exp_f32_e32 v65, v65
	v_rcp_f32_e32 v67, v67
	s_mov_b64 s[40:41], 0
	v_add_f32_e32 v65, 1.0, v65
	v_rcp_f32_e32 v68, v65
	v_add_f32_e32 v65, 1.0, v69
	v_mul_f32_e32 v69, 0xbfb8aa3b, v62
	v_exp_f32_e32 v70, v69
	v_mul_f32_e32 v69, 0xbfb8aa3b, v58
	v_exp_f32_e32 v71, v69
	v_rcp_f32_e32 v69, v65
	v_add_f32_e32 v65, 1.0, v70
	v_rcp_f32_e32 v70, v65
	v_add_f32_e32 v65, 1.0, v71
	v_mul_f32_e32 v71, 0xbfb8aa3b, v63
	v_exp_f32_e32 v72, v71
	v_mul_f32_e32 v71, 0xbfb8aa3b, v59
	v_exp_f32_e32 v74, v71
	v_rcp_f32_e32 v71, v65
	v_add_f32_e32 v65, 1.0, v72
	v_rcp_f32_e32 v73, v65
	v_add_f32_e32 v65, 1.0, v74
	v_rcp_f32_e32 v72, v65

; __device__ __forceinline__ unsigned cvt_pk_bf16(float lo, float hi) { unsigned r; asm volatile("v_cvt_pk_bf16_f32 %0, %1, %2" : "=v"(r) : "v"(lo), "v"(hi)); return r; }
; __device__ __forceinline__ float silu_f(float g) { return g * __builtin_amdgcn_rcpf(1.0f + __expf(-g)); }
; __device__ __forceinline__ float sigm_f(float g) { return __builtin_amdgcn_rcpf(1.0f + __expf(-g)); }
;     __device__ __forceinline__ void operator()(const f32x4 (&acc)[2][2][4][2], const Unit& u, int wr, int wc, int fr, int fq) const {
;     ...
;             for (int m = 0; m < 4; ++m) { const int row = row0 + ai * HALF + m * 16;
;                 const float rs = __builtin_amdgcn_rsqf(ssq[row] * (1.0f / 1024.0f) + 1e-6f);
;                 bf16_t* rowp = O + (size_t)row * 4224 + col0;
; #pragma unroll
;                 for (int bj = 0; bj < 2; ++bj) { f32x4 v0 = acc[ai][bj][m][0] * rs + sv[bj][0], v1 = acc[ai][bj][m][1] * rs + sv[bj][1];
;                     if (mode == 1) {
; #pragma unroll
;                         for (int e = 0; e < 4; ++e) { v0[e] = silu_f(v0[e]); v1[e] = silu_f(v1[e]); }
;                     } else if (mode == 2) {
; #pragma unroll
;                         for (int e = 0; e < 4; ++e) { v0[e] = sigm_f(v0[e]); v1[e] = sigm_f(v1[e]); }
;                     }
;                     u32x4 w; w.x = cvt_pk_bf16(v0[0], v0[1]); w.y = cvt_pk_bf16(v0[2], v0[3]); w.z = cvt_pk_bf16(v1[0], v1[1]); w.w = cvt_pk_bf16(v1[2], v1[3]);
;                     *(u32x4*)(rowp + bj * HALF) = w; } }
.LBB0_272:
	v_cvt_pk_bf16_f32 v48, v58, v60
	v_cvt_pk_bf16_f32 v49, v62, v65
	v_cvt_pk_bf16_f32 v50, v59, v61
	v_cvt_pk_bf16_f32 v51, v63, v64
	global_store_dwordx4 v[56:57], v[48:51], off offset:256
	s_nop 0
	s_cmp_gt_i32 s49, 1
	s_mov_b64 s[40:41], -1
	v_fmamk_f32 v48, v197, 0x3a800000, v224
	v_rsq_f32_e32 v48, v48
	s_nop 0
	v_pk_fma_f32 v[38:39], v[38:39], v[48:49], v[46:47] op_sel_hi:[1,0,1]
	v_pk_fma_f32 v[36:37], v[36:37], v[48:49], v[44:45] op_sel_hi:[1,0,1]
	v_pk_fma_f32 v[34:35], v[34:35], v[48:49], v[42:43] op_sel_hi:[1,0,1]
	v_pk_fma_f32 v[32:33], v[32:33], v[48:49], v[40:41] op_sel_hi:[1,0,1]
	s_cbranch_scc0 .LBB0_274
	v_mul_f32_e32 v49, 0xbfb8aa3b, v36
	v_exp_f32_e32 v49, v49
	v_mul_f32_e32 v50, 0xbfb8aa3b, v32
	v_exp_f32_e32 v50, v50
	v_mul_f32_e32 v52, 0xbfb8aa3b, v33
	v_add_f32_e32 v49, 1.0, v49
	v_exp_f32_e32 v53, v52
	v_add_f32_e32 v51, 1.0, v50
	v_rcp_f32_e32 v50, v49
	v_mul_f32_e32 v49, 0xbfb8aa3b, v37
	v_exp_f32_e32 v49, v49
	v_rcp_f32_e32 v51, v51
	s_mov_b64 s[40:41], 0
	v_add_f32_e32 v49, 1.0, v49
	v_rcp_f32_e32 v52, v49
	v_add_f32_e32 v49, 1.0, v53
	v_mul_f32_e32 v53, 0xbfb8aa3b, v38
	v_exp_f32_e32 v54, v53
	v_mul_f32_e32 v53, 0xbfb8aa3b, v34
	v_exp_f32_e32 v55, v53
	v_rcp_f32_e32 v53, v49
	v_add_f32_e32 v49, 1.0, v54
	v_rcp_f32_e32 v54, v49
	v_add_f32_e32 v49, 1.0, v55
	v_mul_f32_e32 v55, 0xbfb8aa3b, v39
	v_exp_f32_e32 v56, v55
	v_mul_f32_e32 v55, 0xbfb8aa3b, v35
	v_exp_f32_e32 v58, v55
	v_rcp_f32_e32 v55, v49
	v_add_f32_e32 v49, 1.0, v56
	v_rcp_f32_e32 v57, v49
	v_add_f32_e32 v49, 1.0, v58
	v_rcp_f32_e32 v56, v49

; __device__ __forceinline__ unsigned cvt_pk_bf16(float lo, float hi) { unsigned r; asm volatile("v_cvt_pk_bf16_f32 %0, %1, %2" : "=v"(r) : "v"(lo), "v"(hi)); return r; }
; __device__ __forceinline__ float silu_f(float g) { return g * __builtin_amdgcn_rcpf(1.0f + __expf(-g)); }
; __device__ __forceinline__ float sigm_f(float g) { return __builtin_amdgcn_rcpf(1.0f + __expf(-g)); }
;     __device__ __forceinline__ void operator()(const f32x4 (&acc)[2][2][4][2], const Unit& u, int wr, int wc, int fr, int fq) const {
;     ...
;             for (int m = 0; m < 4; ++m) { const int row = row0 + ai * HALF + m * 16;
;                 const float rs = __builtin_amdgcn_rsqf(ssq[row] * (1.0f / 1024.0f) + 1e-6f);
;                 bf16_t* rowp = O + (size_t)row * 4224 + col0;
; #pragma unroll
;                 for (int bj = 0; bj < 2; ++bj) { f32x4 v0 = acc[ai][bj][m][0] * rs + sv[bj][0], v1 = acc[ai][bj][m][1] * rs + sv[bj][1];
;                     if (mode == 1) {
; #pragma unroll
;                         for (int e = 0; e < 4; ++e) { v0[e] = silu_f(v0[e]); v1[e] = silu_f(v1[e]); }
;                     } else if (mode == 2) {
; #pragma unroll
;                         for (int e = 0; e < 4; ++e) { v0[e] = sigm_f(v0[e]); v1[e] = sigm_f(v1[e]); }
;                     }
;                     u32x4 w; w.x = cvt_pk_bf16(v0[0], v0[1]); w.y = cvt_pk_bf16(v0[2], v0[3]); w.z = cvt_pk_bf16(v1[0], v1[1]); w.w = cvt_pk_bf16(v1[2], v1[3]);
;                     *(u32x4*)(rowp + bj * HALF) = w; } }
.LBB0_284:
	v_cvt_pk_bf16_f32 v16, v34, v36
	v_cvt_pk_bf16_f32 v17, v38, v49
	v_cvt_pk_bf16_f32 v18, v35, v37
	v_cvt_pk_bf16_f32 v19, v39, v48
	global_store_dwordx4 v[32:33], v[16:19], off offset:256
	s_nop 0
	s_cmp_gt_i32 s49, 1
	s_mov_b64 s[40:41], -1
	v_fmamk_f32 v16, v198, 0x3a800000, v224
	v_rsq_f32_e32 v16, v16
	s_nop 0
	v_pk_fma_f32 v[14:15], v[14:15], v[16:17], v[46:47] op_sel_hi:[1,0,1]
	v_pk_fma_f32 v[12:13], v[12:13], v[16:17], v[44:45] op_sel_hi:[1,0,1]
	v_pk_fma_f32 v[10:11], v[10:11], v[16:17], v[42:43] op_sel_hi:[1,0,1]
	v_pk_fma_f32 v[8:9], v[8:9], v[16:17], v[40:41] op_sel_hi:[1,0,1]
	s_cbranch_scc0 .LBB0_286
	v_mul_f32_e32 v17, 0xbfb8aa3b, v12
	v_exp_f32_e32 v17, v17
	v_mul_f32_e32 v18, 0xbfb8aa3b, v8
	v_exp_f32_e32 v18, v18
	v_mul_f32_e32 v20, 0xbfb8aa3b, v9
	v_add_f32_e32 v17, 1.0, v17
	v_exp_f32_e32 v21, v20
	v_add_f32_e32 v19, 1.0, v18
	v_rcp_f32_e32 v18, v17
	v_mul_f32_e32 v17, 0xbfb8aa3b, v13
	v_exp_f32_e32 v17, v17
	v_rcp_f32_e32 v19, v19
	s_mov_b64 s[40:41], 0
	v_add_f32_e32 v17, 1.0, v17
	v_rcp_f32_e32 v20, v17
	v_add_f32_e32 v17, 1.0, v21
	v_mul_f32_e32 v21, 0xbfb8aa3b, v14
	v_exp_f32_e32 v22, v21
	v_mul_f32_e32 v21, 0xbfb8aa3b, v10
	v_exp_f32_e32 v23, v21
	v_rcp_f32_e32 v21, v17
	v_add_f32_e32 v17, 1.0, v22
	v_rcp_f32_e32 v22, v17
	v_add_f32_e32 v17, 1.0, v23
	v_mul_f32_e32 v23, 0xbfb8aa3b, v15
	v_exp_f32_e32 v32, v23
	v_mul_f32_e32 v23, 0xbfb8aa3b, v11
	v_exp_f32_e32 v34, v23
	v_rcp_f32_e32 v23, v17
	v_add_f32_e32 v17, 1.0, v32
	v_rcp_f32_e32 v33, v17
	v_add_f32_e32 v17, 1.0, v34
	v_rcp_f32_e32 v32, v17
